# in-projection GEMM: second-round tile of CU c is now the one CU c^1 had (XCD parity swapped) so each CU gets one rotary/cache-heavy tile and one plain tile instead of two heavy or two plain
# speedup vs baseline: 1.0063x; 1.0063x over previous
.LBB0_463:
	s_add_i32 s63, s63, 1
	s_mul_i32 s1, s63, s51
	s_mul_hi_u32 s4, s63, s42
	s_add_i32 s4, s4, s1
	s_mul_i32 s1, s63, s42
	s_add_u32 s56, s1, s2
	s_addc_u32 s57, s4, s43
	s_xor_b32 s56, s56, 1
	v_mov_b64_e32 v[0:1], 0x200
	v_cmp_lt_i64_e64 s[4:5], s[56:57], v[0:1]
	v_mov_b64_e32 v[0:1], 0x1ff
	v_cmp_gt_i64_e32 vcc, s[56:57], v[0:1]
	s_cbranch_vccnz .LBB0_468
	v_mov_b64_e32 v[0:1], 0x15f
	v_cmp_gt_i64_e32 vcc, s[56:57], v[0:1]
	s_mov_b64 s[66:67], -1
	s_cbranch_vccz .LBB0_466
	s_add_i32 s1, s56, 0xa0
	s_and_b32 s13, s56, 7
	s_mul_i32 s13, s13, 20
	s_bfe_u32 s1, s1, 0x50003
	s_add_i32 s1, s1, s13
	s_and_b32 s13, s1, 0xff
	s_mulk_i32 s13, 0xcd
	s_lshr_b32 s13, s13, 13
	s_lshl_b32 s24, s13, 2
	s_and_b32 s22, s24, 28
	s_sub_i32 s22, 16, s22
	s_min_u32 s25, s22, 4
	v_cvt_f32_ubyte0_e32 v0, s25
	v_rcp_iflag_f32_e32 v1, v0
	s_mul_i32 s13, s13, 40
	s_sub_i32 s1, s1, s13
	v_cvt_f32_ubyte0_e32 v2, s1
	v_mul_f32_e32 v1, v2, v1
	v_trunc_f32_e32 v1, v1
	v_cvt_u32_f32_e32 v3, v1
	v_fma_f32 v1, -v1, v0, v2
	v_cmp_ge_f32_e64 s[22:23], |v1|, v0
	s_cmp_lg_u64 s[22:23], 0
	v_readfirstlane_b32 s13, v3
	s_addc_u32 s13, s13, 0
	s_mul_i32 s22, s13, s25
	s_sub_i32 s1, s1, s22
	s_add_i32 s1, s1, s24
	s_and_b32 s22, s1, 0xff
	s_and_b32 s1, s13, 0xff
	s_cmp_gt_u32 s1, 7
	s_cselect_b64 s[24:25], -1, 0
	s_cmp_lg_u64 s[24:25], 0
	s_addc_u32 s24, s1, 0
	s_mov_b64 s[66:67], 0
